# chunk-local phase: 4th round of S5 chunk tasks of the 1024-deep-DFT blocks and gMLP blocks redistributed to the short-DFT blocks and the item-less blocks (512-block grid)
# speedup vs baseline: 1.0124x; 1.0025x over previous
.LBB0_1006:
	s_movk_i32 s43, 0x1000
	s_or_b64 exec, exec, s[70:71]
	v_mov_b32_e32 v14, v231
	ds_read_b64 v[10:11], v229 offset:63760
	ds_read_b64 v[6:7], v229 offset:63760
	ds_read_b64 v[12:13], v229 offset:63760
	ds_read_b64 v[8:9], v229 offset:63760
	s_waitcnt lgkmcnt(0)
	ds_read_b64 v[2:3], v229 offset:63760
	ds_read_b64 v[0:1], v229 offset:63760
	ds_read_b64 v[4:5], v229 offset:63760
	v_ashrrev_i32_e32 v15, 6, v14
	s_mov_b32 s0, s76
	s_nop 0
	v_lshl_add_u32 v55, s0, 2, v15
	v_cmp_gt_i32_e32 vcc, s94, v55
	s_mov_b64 s[0:1], exec
	v_readlane_b32 s78, v255, 13
	s_and_b64 s[2:3], s[0:1], vcc
	s_movk_i32 s22, 0x110
	s_movk_i32 s23, 0x2200
	s_movk_i32 s24, 0x840
	s_movk_i32 s25, 0x210
	s_mov_b32 s26, 0x8800
	s_mov_b32 s27, 0x1780000
	s_movk_i32 s46, 0x1600
	s_mov_b32 s47, 0x84000
	s_mov_b32 s48, 0x58000
	s_mov_b32 s49, 0x2c000
	s_mov_b32 s51, s87
	s_mov_b64 s[52:53], 0x40000
	s_mov_b64 s[54:55], 0x1200000
	s_mov_b64 s[56:57], 0x2ad4000
	s_mov_b64 s[58:59], 0x4ad4000
	s_mov_b64 s[60:61], 0x80
	s_mov_b64 s[62:63], 0x5ad4000
	s_mov_b64 s[64:65], 0x9ad4000
	s_mov_b64 s[66:67], 0x1c00
	s_mov_b32 s68, 0x3b800000
	s_mov_b64 s[70:71], 0x1800
	s_mov_b32 s69, s82
	v_readlane_b32 s79, v255, 14
	s_mov_b64 exec, s[2:3]
	s_cbranch_execz .LBB0_1011
	s_movk_i32 s2, 0x2c00
	v_mul_lo_u32 v67, v15, s2
	s_mov_b64 s[2:3], 0x2a54000
	v_lshl_add_u64 v[46:47], v[12:13], 0, s[2:3]
	s_mov_b64 s[2:3], 0x2a94000
	v_lshl_add_u64 v[48:49], v[8:9], 0, s[2:3]
	s_mov_b64 s[2:3], 0x2a44000
	v_lshl_add_u64 v[50:51], v[6:7], 0, s[2:3]
	v_readlane_b32 s2, v255, 9
	v_and_b32_e32 v228, 48, v14
	v_and_b32_e32 v59, 63, v14
	s_lshl_b32 s4, s2, 5
	s_waitcnt lgkmcnt(0)
	v_lshl_add_u64 v[4:5], v[4:5], 0, v[228:229]
	s_mov_b64 s[2:3], 0xef54000
	v_lshl_add_u64 v[52:53], v[4:5], 0, s[2:3]
	v_lshlrev_b32_e32 v6, 3, v59
	v_lshl_add_u32 v84, v59, 5, v67
	s_movk_i32 s2, 0xffe4
	v_mov_b32_e32 v7, v229
	v_and_b32_e32 v9, 15, v14
	v_mad_i32_i24 v54, v59, s2, v84
	v_lshl_add_u64 v[2:3], v[2:3], 0, v[6:7]
	s_mov_b64 s[2:3], 0xe754000
	v_lshl_add_u64 v[56:57], v[2:3], 0, s[2:3]
	v_or_b32_e32 v2, v67, v228
	v_lshlrev_b32_e32 v228, 2, v9
	v_lshlrev_b32_e32 v4, 10, v14
	v_lshl_add_u64 v[0:1], v[0:1], 0, v[228:229]
	s_mov_b64 s[2:3], 0xa2d4000
	v_lshl_add_u64 v[44:45], v[10:11], 0, s[62:63]
	v_lshlrev_b32_e32 v10, 7, v9
	v_and_b32_e32 v4, 0xf800, v4
	v_and_b32_e32 v8, 8, v6
	v_lshrrev_b32_e32 v3, 2, v14
	v_lshl_add_u64 v[60:61], v[0:1], 0, s[2:3]
	v_mul_u32_u24_e32 v0, 0x110, v9
	v_and_b32_e32 v58, 12, v3
	s_mov_b64 s[2:3], 0
	v_lshlrev_b32_e32 v85, 1, v10
	v_lshlrev_b32_e32 v62, 2, v4
	v_lshlrev_b32_e32 v64, 2, v8
	v_add_u32_e32 v86, v2, v0
	s_mov_b32 s18, s77
	s_mov_b32 s19, s86
	s_mov_b32 s20, 0
	s_cmp_eq_u32 s77, 0x800
	s_cbranch_scc0 .Ls5l_ctl_done
	s_cmpk_lt_u32 s76, 0x100
	s_cbranch_scc1 .Ls5l_ctl_r3
	s_cmpk_lt_u32 s76, 0x140
	s_cbranch_scc1 .Ls5l_ctl_ctx
	s_cmpk_lt_u32 s76, 0x1c0
	s_cbranch_scc1 .Ls5l_ctl_r3
	s_mov_b32 s20, 2
	s_branch .Ls5l_ctl_done
.Ls5l_ctl_ctx:
	s_mov_b32 s20, 3
	s_branch .Ls5l_ctl_done
.Ls5l_ctl_r3:
	s_movk_i32 s19, 0x17ff
.Ls5l_ctl_done:
.LBB0_1008:
	v_bfe_u32 v87, v55, 4, 1
	v_and_b32_e32 v63, 15, v55
	v_lshlrev_b32_e32 v88, 4, v87
	v_or3_b32 v4, v88, s4, v63
	v_lshl_or_b32 v2, v4, 6, v59
	v_lshlrev_b32_e32 v228, 1, v2
	v_lshl_add_u64 v[0:1], v[228:229], 2, v[50:51]
	v_lshlrev_b32_e32 v228, 4, v2
	v_and_b32_e32 v68, 0xffffffe0, v55
	global_load_dwordx2 v[70:71], v[0:1], off
	v_lshlrev_b64 v[0:1], 2, v[228:229]
	v_ashrrev_i32_e32 v69, 31, v68
	v_lshl_add_u64 v[2:3], v[46:47], 0, v[0:1]
	v_lshl_add_u64 v[0:1], v[48:49], 0, v[0:1]
	v_lshl_or_b32 v228, v4, 12, v85
	v_lshlrev_b64 v[72:73], 13, v[68:69]
	global_load_dwordx4 v[32:35], v[2:3], off offset:48
	global_load_dwordx4 v[36:39], v[2:3], off offset:32
	global_load_dwordx4 v[40:43], v[2:3], off offset:16
	global_load_dwordx4 v[90:93], v[2:3], off
	global_load_dwordx4 v[12:15], v[0:1], off offset:48
	global_load_dwordx4 v[16:19], v[0:1], off offset:32
	global_load_dwordx4 v[20:23], v[0:1], off offset:16
	global_load_dwordx4 v[24:27], v[0:1], off
	v_lshl_add_u64 v[0:1], v[52:53], 0, v[228:229]
	v_lshl_add_u64 v[72:73], v[44:45], 0, v[72:73]
	v_lshlrev_b32_e32 v228, 6, v63
	v_lshlrev_b32_e32 v66, 4, v63
	v_lshl_add_u64 v[72:73], v[72:73], 0, v[228:229]
	v_mov_b32_e32 v63, v229
	v_lshl_add_u64 v[72:73], v[72:73], 0, v[62:63]
	v_mov_b32_e32 v65, v229
	global_load_dwordx4 v[28:31], v[0:1], off
	global_load_dwordx4 v[8:11], v[0:1], off offset:64
	global_load_dwordx4 v[4:7], v[0:1], off offset:128
	s_nop 0
	global_load_dwordx4 v[0:3], v[0:1], off offset:192
	v_lshl_add_u64 v[76:77], v[72:73], 0, v[64:65]
	global_load_dwordx4 v[72:75], v[76:77], off offset:16
	s_nop 0
	global_load_dwordx4 v[76:79], v[76:77], off
	s_mov_b32 s5, 0
	v_cmp_eq_u32_e32 vcc, 0, v87
	s_mov_b32 s6, 28
	s_waitcnt vmcnt(0)
	ds_write_b128 v84, v[76:79]
	ds_write_b128 v84, v[72:75] offset:16
	v_and_b32_e32 v208, 31, v59
	v_sub_u32_e32 v209, 31, v208
	v_mov_b32_e32 v217, 0x110
	v_mov_b32_e32 v210, 0xfffffef0
	v_cndmask_b32_e32 v208, v209, v208, vcc
	v_lshrrev_b32_e32 v209, 5, v59
	v_add_u32_e32 v211, 0x20f0, v54
	v_cndmask_b32_e32 v217, v210, v217, vcc
	v_lshlrev_b32_e32 v209, 2, v209
	v_cndmask_b32_e32 v216, v211, v54, vcc
	v_lshl_add_u32 v218, v208, 6, v67
	v_add_u32_e32 v218, v218, v209
	ds_read_b32 v200, v218
	ds_read_b32 v201, v218 offset:8
	ds_read_b32 v202, v218 offset:16
	ds_read_b32 v203, v218 offset:24
	ds_read_b32 v204, v218 offset:32
	ds_read_b32 v205, v218 offset:40
	ds_read_b32 v206, v218 offset:48
	ds_read_b32 v207, v218 offset:56
	v_permlane32_swap_b32_e32 v90, v91
	v_permlane32_swap_b32_e32 v92, v93
	v_permlane32_swap_b32_e32 v40, v41
	v_permlane32_swap_b32_e32 v42, v43
	v_permlane32_swap_b32_e32 v36, v37
	v_permlane32_swap_b32_e32 v38, v39
	v_permlane32_swap_b32_e32 v32, v33
	v_permlane32_swap_b32_e32 v34, v35
	v_permlane32_swap_b32_e32 v24, v25
	v_permlane32_swap_b32_e32 v26, v27
	v_permlane32_swap_b32_e32 v20, v21
	v_permlane32_swap_b32_e32 v22, v23
	v_permlane32_swap_b32_e32 v16, v17
	v_permlane32_swap_b32_e32 v18, v19
	v_permlane32_swap_b32_e32 v12, v13
	v_permlane32_swap_b32_e32 v14, v15
	s_waitcnt lgkmcnt(0)
	s_nop 1
	v_mfma_f32_32x32x2_f32 v[136:151], v200, v90, 0
	v_mfma_f32_32x32x2_f32 v[136:151], v201, v92, v[136:151]
	v_mfma_f32_32x32x2_f32 v[136:151], v202, v40, v[136:151]
	v_mfma_f32_32x32x2_f32 v[136:151], v203, v42, v[136:151]
	v_mfma_f32_32x32x2_f32 v[136:151], v204, v36, v[136:151]
	v_mfma_f32_32x32x2_f32 v[136:151], v205, v38, v[136:151]
	v_mfma_f32_32x32x2_f32 v[136:151], v206, v32, v[136:151]
	v_mfma_f32_32x32x2_f32 v[136:151], v207, v34, v[136:151]
	v_mfma_f32_32x32x2_f32 v[152:167], v200, v91, 0
	v_mfma_f32_32x32x2_f32 v[152:167], v201, v93, v[152:167]
	v_mfma_f32_32x32x2_f32 v[152:167], v202, v41, v[152:167]
	v_mfma_f32_32x32x2_f32 v[152:167], v203, v43, v[152:167]
	v_mfma_f32_32x32x2_f32 v[152:167], v204, v37, v[152:167]
	v_mfma_f32_32x32x2_f32 v[152:167], v205, v39, v[152:167]
	v_mfma_f32_32x32x2_f32 v[152:167], v206, v33, v[152:167]
	v_mfma_f32_32x32x2_f32 v[152:167], v207, v35, v[152:167]
	v_mfma_f32_32x32x2_f32 v[168:183], v200, v24, 0
	v_mfma_f32_32x32x2_f32 v[168:183], v201, v26, v[168:183]
	v_mfma_f32_32x32x2_f32 v[168:183], v202, v20, v[168:183]
	v_mfma_f32_32x32x2_f32 v[168:183], v203, v22, v[168:183]
	v_mfma_f32_32x32x2_f32 v[168:183], v204, v16, v[168:183]
	v_mfma_f32_32x32x2_f32 v[168:183], v205, v18, v[168:183]
	v_mfma_f32_32x32x2_f32 v[168:183], v206, v12, v[168:183]
	v_mfma_f32_32x32x2_f32 v[168:183], v207, v14, v[168:183]
	v_mfma_f32_32x32x2_f32 v[184:199], v200, v25, 0
	v_mfma_f32_32x32x2_f32 v[184:199], v201, v27, v[184:199]
	v_mfma_f32_32x32x2_f32 v[184:199], v202, v21, v[184:199]
	v_mfma_f32_32x32x2_f32 v[184:199], v203, v23, v[184:199]
	v_mfma_f32_32x32x2_f32 v[184:199], v204, v17, v[184:199]
	v_mfma_f32_32x32x2_f32 v[184:199], v205, v19, v[184:199]
	v_mfma_f32_32x32x2_f32 v[184:199], v206, v13, v[184:199]
	v_mfma_f32_32x32x2_f32 v[184:199], v207, v15, v[184:199]
	s_nop 15
	s_nop 3
	v_permlane32_swap_b32_e32 v136, v152
	v_permlane32_swap_b32_e32 v137, v153
	v_permlane32_swap_b32_e32 v138, v154
	v_permlane32_swap_b32_e32 v139, v155
	v_permlane32_swap_b32_e32 v140, v156
	v_permlane32_swap_b32_e32 v141, v157
	v_permlane32_swap_b32_e32 v142, v158
	v_permlane32_swap_b32_e32 v143, v159
	v_permlane32_swap_b32_e32 v144, v160
	v_permlane32_swap_b32_e32 v145, v161
	v_permlane32_swap_b32_e32 v146, v162
	v_permlane32_swap_b32_e32 v147, v163
	v_permlane32_swap_b32_e32 v148, v164
	v_permlane32_swap_b32_e32 v149, v165
	v_permlane32_swap_b32_e32 v150, v166
	v_permlane32_swap_b32_e32 v151, v167
	v_permlane32_swap_b32_e32 v168, v184
	v_permlane32_swap_b32_e32 v169, v185
	v_permlane32_swap_b32_e32 v170, v186
	v_permlane32_swap_b32_e32 v171, v187
	v_permlane32_swap_b32_e32 v172, v188
	v_permlane32_swap_b32_e32 v173, v189
	v_permlane32_swap_b32_e32 v174, v190
	v_permlane32_swap_b32_e32 v175, v191
	v_permlane32_swap_b32_e32 v176, v192
	v_permlane32_swap_b32_e32 v177, v193
	v_permlane32_swap_b32_e32 v178, v194
	v_permlane32_swap_b32_e32 v179, v195
	v_permlane32_swap_b32_e32 v180, v196
	v_permlane32_swap_b32_e32 v181, v197
	v_permlane32_swap_b32_e32 v182, v198
	v_permlane32_swap_b32_e32 v183, v199
	v_mov_b32_e32 v32, 0
	v_mov_b32_e32 v33, 0
	v_mul_f32_e32 v208, v71, v33
	v_mul_f32_e32 v209, v71, v32
	v_fma_f32 v32, v70, v32, -v208
	v_fma_f32 v33, v70, v33, v209
	v_add_f32_e32 v32, v32, v136
	v_add_f32_e32 v33, v33, v168
	v_cvt_pk_bf16_f32 v210, v32, v33
	ds_write_b32 v216, v210 offset:2048
	v_add_u32_e32 v216, v216, v217
	v_mul_f32_e32 v208, v71, v33
	v_mul_f32_e32 v209, v71, v32
	v_fma_f32 v32, v70, v32, -v208
	v_fma_f32 v33, v70, v33, v209
	v_add_f32_e32 v32, v32, v137
	v_add_f32_e32 v33, v33, v169
	v_cvt_pk_bf16_f32 v210, v32, v33
	ds_write_b32 v216, v210 offset:2048
	v_add_u32_e32 v216, v216, v217
	v_mul_f32_e32 v208, v71, v33
	v_mul_f32_e32 v209, v71, v32
	v_fma_f32 v32, v70, v32, -v208
	v_fma_f32 v33, v70, v33, v209
	v_add_f32_e32 v32, v32, v138
	v_add_f32_e32 v33, v33, v170
	v_cvt_pk_bf16_f32 v210, v32, v33
	ds_write_b32 v216, v210 offset:2048
	v_add_u32_e32 v216, v216, v217
	v_mul_f32_e32 v208, v71, v33
	v_mul_f32_e32 v209, v71, v32
	v_fma_f32 v32, v70, v32, -v208
	v_fma_f32 v33, v70, v33, v209
	v_add_f32_e32 v32, v32, v139
	v_add_f32_e32 v33, v33, v171
	v_cvt_pk_bf16_f32 v210, v32, v33
	ds_write_b32 v216, v210 offset:2048
	v_add_u32_e32 v216, v216, v217
	v_mul_f32_e32 v208, v71, v33
	v_mul_f32_e32 v209, v71, v32
	v_fma_f32 v32, v70, v32, -v208
	v_fma_f32 v33, v70, v33, v209
	v_add_f32_e32 v32, v32, v152
	v_add_f32_e32 v33, v33, v184
	v_cvt_pk_bf16_f32 v210, v32, v33
	ds_write_b32 v216, v210 offset:2048
	v_add_u32_e32 v216, v216, v217
	v_mul_f32_e32 v208, v71, v33
	v_mul_f32_e32 v209, v71, v32
	v_fma_f32 v32, v70, v32, -v208
	v_fma_f32 v33, v70, v33, v209
	v_add_f32_e32 v32, v32, v153
	v_add_f32_e32 v33, v33, v185
	v_cvt_pk_bf16_f32 v210, v32, v33
	ds_write_b32 v216, v210 offset:2048
	v_add_u32_e32 v216, v216, v217
	v_mul_f32_e32 v208, v71, v33
	v_mul_f32_e32 v209, v71, v32
	v_fma_f32 v32, v70, v32, -v208
	v_fma_f32 v33, v70, v33, v209
	v_add_f32_e32 v32, v32, v154
	v_add_f32_e32 v33, v33, v186
	v_cvt_pk_bf16_f32 v210, v32, v33
	ds_write_b32 v216, v210 offset:2048
	v_add_u32_e32 v216, v216, v217
	v_mul_f32_e32 v208, v71, v33
	v_mul_f32_e32 v209, v71, v32
	v_fma_f32 v32, v70, v32, -v208
	v_fma_f32 v33, v70, v33, v209
	v_add_f32_e32 v32, v32, v155
	v_add_f32_e32 v33, v33, v187
	v_cvt_pk_bf16_f32 v210, v32, v33
	ds_write_b32 v216, v210 offset:2048
	v_add_u32_e32 v216, v216, v217
	v_mul_f32_e32 v208, v71, v33
	v_mul_f32_e32 v209, v71, v32
	v_fma_f32 v32, v70, v32, -v208
	v_fma_f32 v33, v70, v33, v209
	v_add_f32_e32 v32, v32, v140
	v_add_f32_e32 v33, v33, v172
	v_cvt_pk_bf16_f32 v210, v32, v33
	ds_write_b32 v216, v210 offset:2048
	v_add_u32_e32 v216, v216, v217
	v_mul_f32_e32 v208, v71, v33
	v_mul_f32_e32 v209, v71, v32
	v_fma_f32 v32, v70, v32, -v208
	v_fma_f32 v33, v70, v33, v209
	v_add_f32_e32 v32, v32, v141
	v_add_f32_e32 v33, v33, v173
	v_cvt_pk_bf16_f32 v210, v32, v33
	ds_write_b32 v216, v210 offset:2048
	v_add_u32_e32 v216, v216, v217
	v_mul_f32_e32 v208, v71, v33
	v_mul_f32_e32 v209, v71, v32
	v_fma_f32 v32, v70, v32, -v208
	v_fma_f32 v33, v70, v33, v209
	v_add_f32_e32 v32, v32, v142
	v_add_f32_e32 v33, v33, v174
	v_cvt_pk_bf16_f32 v210, v32, v33
	ds_write_b32 v216, v210 offset:2048
	v_add_u32_e32 v216, v216, v217
	v_mul_f32_e32 v208, v71, v33
	v_mul_f32_e32 v209, v71, v32
	v_fma_f32 v32, v70, v32, -v208
	v_fma_f32 v33, v70, v33, v209
	v_add_f32_e32 v32, v32, v143
	v_add_f32_e32 v33, v33, v175
	v_cvt_pk_bf16_f32 v210, v32, v33
	ds_write_b32 v216, v210 offset:2048
	v_add_u32_e32 v216, v216, v217
	v_mul_f32_e32 v208, v71, v33
	v_mul_f32_e32 v209, v71, v32
	v_fma_f32 v32, v70, v32, -v208
	v_fma_f32 v33, v70, v33, v209
	v_add_f32_e32 v32, v32, v156
	v_add_f32_e32 v33, v33, v188
	v_cvt_pk_bf16_f32 v210, v32, v33
	ds_write_b32 v216, v210 offset:2048
	v_add_u32_e32 v216, v216, v217
	v_mul_f32_e32 v208, v71, v33
	v_mul_f32_e32 v209, v71, v32
	v_fma_f32 v32, v70, v32, -v208
	v_fma_f32 v33, v70, v33, v209
	v_add_f32_e32 v32, v32, v157
	v_add_f32_e32 v33, v33, v189
	v_cvt_pk_bf16_f32 v210, v32, v33
	ds_write_b32 v216, v210 offset:2048
	v_add_u32_e32 v216, v216, v217
	v_mul_f32_e32 v208, v71, v33
	v_mul_f32_e32 v209, v71, v32
	v_fma_f32 v32, v70, v32, -v208
	v_fma_f32 v33, v70, v33, v209
	v_add_f32_e32 v32, v32, v158
	v_add_f32_e32 v33, v33, v190
	v_cvt_pk_bf16_f32 v210, v32, v33
	ds_write_b32 v216, v210 offset:2048
	v_add_u32_e32 v216, v216, v217
	v_mul_f32_e32 v208, v71, v33
	v_mul_f32_e32 v209, v71, v32
	v_fma_f32 v32, v70, v32, -v208
	v_fma_f32 v33, v70, v33, v209
	v_add_f32_e32 v32, v32, v159
	v_add_f32_e32 v33, v33, v191
	v_cvt_pk_bf16_f32 v210, v32, v33
	ds_write_b32 v216, v210 offset:2048
	v_add_u32_e32 v216, v216, v217
	v_mul_f32_e32 v208, v71, v33
	v_mul_f32_e32 v209, v71, v32
	v_fma_f32 v32, v70, v32, -v208
	v_fma_f32 v33, v70, v33, v209
	v_add_f32_e32 v32, v32, v144
	v_add_f32_e32 v33, v33, v176
	v_cvt_pk_bf16_f32 v210, v32, v33
	ds_write_b32 v216, v210 offset:2048
	v_add_u32_e32 v216, v216, v217
	v_mul_f32_e32 v208, v71, v33
	v_mul_f32_e32 v209, v71, v32
	v_fma_f32 v32, v70, v32, -v208
	v_fma_f32 v33, v70, v33, v209
	v_add_f32_e32 v32, v32, v145
	v_add_f32_e32 v33, v33, v177
	v_cvt_pk_bf16_f32 v210, v32, v33
	ds_write_b32 v216, v210 offset:2048
	v_add_u32_e32 v216, v216, v217
	v_mul_f32_e32 v208, v71, v33
	v_mul_f32_e32 v209, v71, v32
	v_fma_f32 v32, v70, v32, -v208
	v_fma_f32 v33, v70, v33, v209
	v_add_f32_e32 v32, v32, v146
	v_add_f32_e32 v33, v33, v178
	v_cvt_pk_bf16_f32 v210, v32, v33
	ds_write_b32 v216, v210 offset:2048
	v_add_u32_e32 v216, v216, v217
	v_mul_f32_e32 v208, v71, v33
	v_mul_f32_e32 v209, v71, v32
	v_fma_f32 v32, v70, v32, -v208
	v_fma_f32 v33, v70, v33, v209
	v_add_f32_e32 v32, v32, v147
	v_add_f32_e32 v33, v33, v179
	v_cvt_pk_bf16_f32 v210, v32, v33
	ds_write_b32 v216, v210 offset:2048
	v_add_u32_e32 v216, v216, v217
	v_mul_f32_e32 v208, v71, v33
	v_mul_f32_e32 v209, v71, v32
	v_fma_f32 v32, v70, v32, -v208
	v_fma_f32 v33, v70, v33, v209
	v_add_f32_e32 v32, v32, v160
	v_add_f32_e32 v33, v33, v192
	v_cvt_pk_bf16_f32 v210, v32, v33
	ds_write_b32 v216, v210 offset:2048
	v_add_u32_e32 v216, v216, v217
	v_mul_f32_e32 v208, v71, v33
	v_mul_f32_e32 v209, v71, v32
	v_fma_f32 v32, v70, v32, -v208
	v_fma_f32 v33, v70, v33, v209
	v_add_f32_e32 v32, v32, v161
	v_add_f32_e32 v33, v33, v193
	v_cvt_pk_bf16_f32 v210, v32, v33
	ds_write_b32 v216, v210 offset:2048
	v_add_u32_e32 v216, v216, v217
	v_mul_f32_e32 v208, v71, v33
	v_mul_f32_e32 v209, v71, v32
	v_fma_f32 v32, v70, v32, -v208
	v_fma_f32 v33, v70, v33, v209
	v_add_f32_e32 v32, v32, v162
	v_add_f32_e32 v33, v33, v194
	v_cvt_pk_bf16_f32 v210, v32, v33
	ds_write_b32 v216, v210 offset:2048
	v_add_u32_e32 v216, v216, v217
	v_mul_f32_e32 v208, v71, v33
	v_mul_f32_e32 v209, v71, v32
	v_fma_f32 v32, v70, v32, -v208
	v_fma_f32 v33, v70, v33, v209
	v_add_f32_e32 v32, v32, v163
	v_add_f32_e32 v33, v33, v195
	v_cvt_pk_bf16_f32 v210, v32, v33
	ds_write_b32 v216, v210 offset:2048
	v_add_u32_e32 v216, v216, v217
	v_mul_f32_e32 v208, v71, v33
	v_mul_f32_e32 v209, v71, v32
	v_fma_f32 v32, v70, v32, -v208
	v_fma_f32 v33, v70, v33, v209
	v_add_f32_e32 v32, v32, v148
	v_add_f32_e32 v33, v33, v180
	v_cvt_pk_bf16_f32 v210, v32, v33
	ds_write_b32 v216, v210 offset:2048
	v_add_u32_e32 v216, v216, v217
	v_mul_f32_e32 v208, v71, v33
	v_mul_f32_e32 v209, v71, v32
	v_fma_f32 v32, v70, v32, -v208
	v_fma_f32 v33, v70, v33, v209
	v_add_f32_e32 v32, v32, v149
	v_add_f32_e32 v33, v33, v181
	v_cvt_pk_bf16_f32 v210, v32, v33
	ds_write_b32 v216, v210 offset:2048
	v_add_u32_e32 v216, v216, v217
	v_mul_f32_e32 v208, v71, v33
	v_mul_f32_e32 v209, v71, v32
	v_fma_f32 v32, v70, v32, -v208
	v_fma_f32 v33, v70, v33, v209
	v_add_f32_e32 v32, v32, v150
	v_add_f32_e32 v33, v33, v182
	v_cvt_pk_bf16_f32 v210, v32, v33
	ds_write_b32 v216, v210 offset:2048
	v_add_u32_e32 v216, v216, v217
	v_mul_f32_e32 v208, v71, v33
	v_mul_f32_e32 v209, v71, v32
	v_fma_f32 v32, v70, v32, -v208
	v_fma_f32 v33, v70, v33, v209
	v_add_f32_e32 v32, v32, v151
	v_add_f32_e32 v33, v33, v183
	v_cvt_pk_bf16_f32 v210, v32, v33
	ds_write_b32 v216, v210 offset:2048
	v_add_u32_e32 v216, v216, v217
	v_mul_f32_e32 v208, v71, v33
	v_mul_f32_e32 v209, v71, v32
	v_fma_f32 v32, v70, v32, -v208
	v_fma_f32 v33, v70, v33, v209
	v_add_f32_e32 v32, v32, v164
	v_add_f32_e32 v33, v33, v196
	v_cvt_pk_bf16_f32 v210, v32, v33
	ds_write_b32 v216, v210 offset:2048
	v_add_u32_e32 v216, v216, v217
	v_mul_f32_e32 v208, v71, v33
	v_mul_f32_e32 v209, v71, v32
	v_fma_f32 v32, v70, v32, -v208
	v_fma_f32 v33, v70, v33, v209
	v_add_f32_e32 v32, v32, v165
	v_add_f32_e32 v33, v33, v197
	v_cvt_pk_bf16_f32 v210, v32, v33
	ds_write_b32 v216, v210 offset:2048
	v_add_u32_e32 v216, v216, v217
	v_mul_f32_e32 v208, v71, v33
	v_mul_f32_e32 v209, v71, v32
	v_fma_f32 v32, v70, v32, -v208
	v_fma_f32 v33, v70, v33, v209
	v_add_f32_e32 v32, v32, v166
	v_add_f32_e32 v33, v33, v198
	v_cvt_pk_bf16_f32 v210, v32, v33
	ds_write_b32 v216, v210 offset:2048
	v_add_u32_e32 v216, v216, v217
	v_mul_f32_e32 v208, v71, v33
	v_mul_f32_e32 v209, v71, v32
	v_fma_f32 v32, v70, v32, -v208
	v_fma_f32 v33, v70, v33, v209
	v_add_f32_e32 v32, v32, v167
	v_add_f32_e32 v33, v33, v199
	v_cvt_pk_bf16_f32 v210, v32, v33
	ds_write_b32 v216, v210 offset:2048
	s_movk_i32 s5, 0xffef
	v_and_or_b32 v12, v55, s5, v88
	v_ashrrev_i32_e32 v13, 31, v12
	v_lshlrev_b64 v[12:13], 9, v[12:13]
	v_lshl_add_u64 v[12:13], v[56:57], 0, v[12:13]
	global_store_dwordx2 v[12:13], v[32:33], off
	ds_read_b128 v[12:15], v86 offset:2048
	ds_read_b128 v[20:23], v86 offset:2112
	ds_read_b128 v[16:19], v86 offset:6400
	v_lshlrev_b32_e32 v228, 13, v87
	v_add_u32_e32 v55, s18, v55
	v_cmp_lt_i32_e32 vcc, s19, v55
	s_or_b64 s[2:3], vcc, s[2:3]
	s_waitcnt lgkmcnt(2)
	v_mfma_f32_16x16x32_bf16 v[12:15], v[12:15], v[28:31], 0
	s_waitcnt lgkmcnt(1)
	v_mfma_f32_16x16x32_bf16 v[12:15], v[20:23], v[8:11], v[12:15]
	ds_read_b128 v[20:23], v86 offset:6464
	s_waitcnt lgkmcnt(1)
	v_mfma_f32_16x16x32_bf16 v[16:19], v[16:19], v[28:31], 0
	s_waitcnt lgkmcnt(0)
	v_mfma_f32_16x16x32_bf16 v[8:11], v[20:23], v[8:11], v[16:19]
	s_nop 5
	ds_read_b128 v[16:19], v86 offset:2176
	s_waitcnt lgkmcnt(0)
	v_mfma_f32_16x16x32_bf16 v[12:15], v[16:19], v[4:7], v[12:15]
	ds_read_b128 v[16:19], v86 offset:6528
	s_waitcnt lgkmcnt(0)
	v_mfma_f32_16x16x32_bf16 v[4:7], v[16:19], v[4:7], v[8:11]
	s_nop 2
	ds_read_b128 v[8:11], v86 offset:2240
	s_waitcnt lgkmcnt(0)
	v_mfma_f32_16x16x32_bf16 v[8:11], v[8:11], v[0:3], v[12:15]
	s_nop 2
	ds_read_b128 v[12:15], v86 offset:6592
	s_waitcnt lgkmcnt(0)
	v_mfma_f32_16x16x32_bf16 v[0:3], v[12:15], v[0:3], v[4:7]
	s_nop 2
	v_lshl_add_u64 v[4:5], v[228:229], 0, v[68:69]
	v_or_b32_e32 v4, v4, v58
	v_lshlrev_b32_e32 v228, 2, v66
	v_lshl_add_u64 v[6:7], v[60:61], 0, v[228:229]
	v_lshlrev_b64 v[4:5], 10, v[4:5]
	v_lshl_add_u64 v[12:13], v[6:7], 0, v[4:5]
	global_store_dword v[12:13], v8, off
	global_store_dword v[12:13], v9, off offset:1024
	global_store_dword v[12:13], v10, off offset:2048
	global_store_dword v[12:13], v11, off offset:3072
	v_or_b32_e32 v8, 0x4000, v4
	v_mov_b32_e32 v9, v5
	v_lshl_add_u64 v[8:9], v[6:7], 0, v[8:9]
	global_store_dword v[8:9], v0, off
	v_or_b32_e32 v8, 0x4400, v4
	v_mov_b32_e32 v9, v5
	v_lshl_add_u64 v[8:9], v[6:7], 0, v[8:9]
	global_store_dword v[8:9], v1, off
	v_or_b32_e32 v0, 0x4800, v4
	v_mov_b32_e32 v1, v5
	v_lshl_add_u64 v[0:1], v[6:7], 0, v[0:1]
	v_or_b32_e32 v4, 0x4c00, v4
	global_store_dword v[0:1], v2, off
	v_lshl_add_u64 v[0:1], v[6:7], 0, v[4:5]
	global_store_dword v[0:1], v3, off
	s_andn2_b64 exec, exec, s[2:3]
	s_cbranch_execnz .LBB0_1008
	s_cmp_eq_u32 s20, 0
	s_cbranch_scc1 .LBB0_1011
	s_movk_i32 s18, 0x100
	s_mov_b64 exec, s[0:1]
	s_mov_b64 s[2:3], 0
	v_lshrrev_b32_e32 v55, 6, v231
	s_cmp_eq_u32 s20, 3
	s_cbranch_scc0 .Ls5l_x_idle
	s_sub_i32 s21, s76, 0x100
	s_lshl_b32 s21, s21, 2
	s_addk_i32 s21, 0x1800
	s_movk_i32 s19, 0x19ff
	s_mov_b32 s20, 0
	s_branch .Ls5l_x_go
.Ls5l_x_idle:
	s_sub_i32 s21, s76, 0x1c0
	s_lshl_b32 s21, s21, 2
	s_cmp_eq_u32 s20, 2
	s_cbranch_scc0 .Ls5l_x_idle2
	s_addk_i32 s21, 0x1a00
	s_movk_i32 s19, 0x1bff
	s_mov_b32 s20, 1
	s_branch .Ls5l_x_go
.Ls5l_x_idle2:
	s_addk_i32 s21, 0x1d00
	s_movk_i32 s19, 0x1eff
	s_mov_b32 s20, 0
.Ls5l_x_go:
	v_add_u32_e32 v55, s21, v55
	s_branch .LBB0_1008
